# on v69: P4/P12 LayerNorm passes, join and loop-top vmcnt(0) replaced by counted waits (first entry drained in front of the loops)
# speedup vs baseline: 1.0028x; 1.0028x over previous
; #define LAS __attribute__((address_space(3)))
; __device__ __forceinline__ unsigned cvt_pk_bf16(float lo, float hi) { const f32x2 v = (f32x2){lo, hi}; const bf16v2 b = __builtin_convertvector(v, bf16v2); return __builtin_bit_cast(unsigned, b); }
; template <int PH>
; __device__ __forceinline__ void ln_pass(const Params& p, LAS unsigned char* lds, unsigned char* ws, float* Yx, float* Yc, const float* modv, const float* lng, const float* lnb, f32x2* st1, f32x2* st2, bf16_t* R0, int gw, int NGW, int lane, int wave) {
;     ...
;             { const int tid_ = (int)threadIdx.x; *(LAS f32x4*)(Lg + tid_ * 4) = *(const f32x4*)(lg + tid_ * 4); *(LAS f32x4*)(Lb + tid_ * 4) = *(const f32x4*)(lb + tid_ * 4); }
;             int cur_mr = -1;
;             f32x4 nv[8];
;             if (gw < rows) { const float* y0 = gw < MX ? Yx + (size_t)gw * D : p.in[I_CTX] + (size_t)(gw - MX) * D;
; #pragma unroll
;                 for (int q = 0; q < 8; ++q) nv[q] = *(const f32x4*)(y0 + q * 256 + lane * 4); }
;     ...
;                 bf16_t* o = R0 + (size_t)m * D;
; #pragma unroll
;                 for (int hq = 0; hq < 2; ++hq) {
;                     f32x4 g4[4], b4[4], s4[4], t4[4];
; #pragma unroll
;                     for (int u = 0; u < 4; ++u) { const int c = (hq * 4 + u) * 256 + lane * 4; g4[u] = *(const LAS f32x4*)(Lg + c); b4[u] = *(const LAS f32x4*)(Lb + c); s4[u] = *(const LAS f32x4*)(Ls + c); t4[u] = *(const LAS f32x4*)(Lt + c); }
; #pragma unroll
;                     for (int u = 0; u < 4; ++u) { const int q = hq * 4 + u, c = q * 256 + lane * 4;
;                         const f32x4 xn = v[q] * rstd * g4[u] + b4[u];
;                         const f32x4 h = xn * (1.0f + s4[u]) + t4[u];
;                         u32x2 w; w.x = cvt_pk_bf16(h[0], h[1]); w.y = cvt_pk_bf16(h[2], h[3]); *(u32x2*)(o + c) = w; }
.LBB0_375:
	s_cmp_lt_i32 s90, 5
	s_cselect_b64 s[2:3], -1, 0
	s_and_b64 s[4:5], s[2:3], s[0:1]
	s_andn2_b64 vcc, exec, s[4:5]
	s_cbranch_vccnz .LBB0_385
	global_load_dwordx4 v[0:3], v180, s[48:49]
	global_load_dwordx4 v[4:7], v180, s[50:51]
	s_mov_b32 s7, 0
	v_add_u32_e32 v94, 0, v180
	s_cmp_gt_i32 s34, 0x87ff
	s_waitcnt vmcnt(0)
	ds_write_b128 v94, v[0:3]
	ds_write_b128 v94, v[4:7] offset:8192
	s_cbranch_scc1 .LBB0_385
	s_ashr_i32 s35, s34, 31
	s_add_i32 s0, s34, 0xffff8000
	s_cmp_lt_i32 s34, 0x8000
	s_cselect_b32 s1, s35, 0
	s_cselect_b32 s0, s34, s0
	s_cselect_b32 s2, s87, s41
	s_cselect_b32 s3, s86, s40
	s_lshl_b64 s[0:1], s[0:1], 13
	s_add_u32 s0, s3, s0
	v_mov_b32_e32 v69, 0
	v_lshlrev_b32_e32 v68, 4, v240
	s_addc_u32 s1, s2, s1
	v_lshl_add_u64 v[0:1], s[0:1], 0, v[68:69]
	s_movk_i32 s17, 0x1000
	v_add_co_u32_e32 v0, vcc, s17, v0
	global_load_dwordx4 v[56:59], v68, s[0:1]
	global_load_dwordx4 v[60:63], v68, s[0:1] offset:1024
	global_load_dwordx4 v[36:39], v68, s[0:1] offset:2048
	global_load_dwordx4 v[16:19], v68, s[0:1] offset:3072
	v_addc_co_u32_e32 v1, vcc, 0, v1, vcc
	global_load_dwordx4 v[12:15], v[0:1], off
	global_load_dwordx4 v[8:11], v[0:1], off offset:1024
	global_load_dwordx4 v[4:7], v[0:1], off offset:2048
	s_nop 0
	global_load_dwordx4 v[0:3], v[0:1], off offset:3072
	v_lshl_add_u64 v[22:23], s[88:89], 0, v[68:69]
	s_mov_b64 s[0:1], 0x27400000
	v_lshl_add_u64 v[70:71], v[22:23], 0, s[0:1]
	s_mov_b64 s[0:1], 0x194000
	v_lshl_add_u64 v[72:73], v[22:23], 0, s[0:1]
	s_mov_b64 s[0:1], 0x195000
	v_lshl_add_u64 v[74:75], v[22:23], 0, s[0:1]
	s_mov_b64 s[0:1], 0x195400
	v_lshl_add_u64 v[76:77], v[22:23], 0, s[0:1]
	s_mov_b64 s[0:1], 0x195800
	v_lshl_add_u64 v[78:79], v[22:23], 0, s[0:1]
	s_mov_b64 s[0:1], 0x195c00
	v_lshl_add_u64 v[80:81], v[22:23], 0, s[0:1]
	v_mbcnt_lo_u32_b32 v22, -1, 0
	v_mbcnt_hi_u32_b32 v22, -1, v22
	v_and_b32_e32 v24, 64, v22
	v_xor_b32_e32 v23, 16, v22
	v_add_u32_e32 v24, 64, v24
	v_cmp_lt_i32_e32 vcc, v23, v24
	s_lshl_b64 s[0:1], s[34:35], 3
	s_add_u32 s22, s0, 0x200000
	v_cndmask_b32_e32 v23, v22, v23, vcc
	v_lshlrev_b32_e32 v96, 2, v23
	v_xor_b32_e32 v23, 32, v22
	v_cmp_lt_i32_e32 vcc, v23, v24
	v_lshlrev_b32_e32 v21, 2, v241
	v_lshlrev_b32_e32 v20, 2, v240
	v_cndmask_b32_e32 v22, v22, v23, vcc
	s_addc_u32 s23, s1, 0
	s_ashr_i32 s31, s30, 31
	s_lshl_b64 s[0:1], s[34:35], 12
	v_cmp_eq_u32_e64 s[2:3], 0, v240
	v_add_u32_e32 v95, 0, v68
	s_mov_b32 s33, -1
	v_lshlrev_b32_e32 v97, 2, v22
	s_lshl_b64 s[8:9], s[30:31], 3
	v_lshl_or_b32 v82, v240, 3, s0
	v_mov_b32_e32 v83, s1
	s_lshl_b64 s[10:11], s[30:31], 12
	v_lshlrev_b32_e32 v84, 2, v21
	v_lshlrev_b32_e32 v68, 2, v20
	s_mov_b32 s16, 0x3f9837f0
	s_mov_b32 s31, 0x1001000
	s_mov_b32 s35, 0x2001000
	s_mov_b32 s36, 0x3001000
	v_mov_b32_e32 v98, 0x3727c5ac
	s_mov_b32 s37, 0xf800000
	v_mov_b32_e32 v99, 0x260
	s_mov_b32 s42, 0x7600000
	s_mov_b32 s0, s34
	s_waitcnt vmcnt(0)
	s_branch .LBB0_379
.LBB0_378:
	s_or_b64 exec, exec, s[0:1]
	v_mov_b32_e32 v156, v65
	v_mov_b32_e32 v157, v57
	v_mov_b32_e32 v160, v67
	v_mov_b32_e32 v161, v59
	v_mov_b32_e32 v13, v86
	ds_read_b128 v[86:89], v95
	ds_read_b128 v[90:93], v95 offset:1024
	ds_read_b128 v[100:103], v95 offset:8192
	ds_read_b128 v[104:107], v95 offset:9216
	ds_read_b128 v[108:111], v95 offset:16384
	ds_read_b128 v[112:115], v95 offset:17408
	ds_read_b128 v[116:119], v95 offset:24576
	ds_read_b128 v[120:123], v95 offset:25600
	ds_read_b128 v[124:127], v95 offset:2048
	ds_read_b128 v[128:131], v95 offset:3072
	ds_read_b128 v[132:135], v95 offset:10240
	ds_read_b128 v[136:139], v95 offset:11264
	ds_read_b128 v[140:143], v95 offset:18432
	ds_read_b128 v[144:147], v95 offset:19456
	ds_read_b128 v[148:151], v95 offset:26624
	ds_read_b128 v[152:155], v95 offset:27648
	v_pk_mul_f32 v[160:161], v[160:161], v[10:11] op_sel_hi:[1,0]
	v_pk_mul_f32 v[156:157], v[156:157], v[10:11] op_sel_hi:[1,0]
	s_waitcnt lgkmcnt(13)
	v_pk_fma_f32 v[88:89], v[160:161], v[88:89], v[102:103]
	v_pk_fma_f32 v[86:87], v[156:157], v[86:87], v[100:101]
	s_waitcnt lgkmcnt(11)
	v_pk_add_f32 v[100:101], v[110:111], 1.0 op_sel_hi:[1,0]
	v_pk_add_f32 v[102:103], v[108:109], 1.0 op_sel_hi:[1,0]
	s_waitcnt lgkmcnt(9)
	v_pk_fma_f32 v[88:89], v[88:89], v[100:101], v[118:119]
	v_pk_fma_f32 v[86:87], v[86:87], v[102:103], v[116:117]
	v_mov_b32_e32 v65, v56
	v_cvt_pk_bf16_f32 v86, v86, v87
	v_cvt_pk_bf16_f32 v87, v88, v89
	v_lshl_add_u64 v[88:89], s[88:89], 0, v[82:83]
	v_add_co_u32_e32 v156, vcc, s42, v88
	v_mov_b32_e32 v67, v58
	s_nop 0
	v_addc_co_u32_e32 v157, vcc, 0, v89, vcc
	v_pk_mul_f32 v[58:59], v[66:67], v[10:11] op_sel_hi:[1,0]
	v_pk_mul_f32 v[64:65], v[64:65], v[10:11] op_sel_hi:[1,0]
	v_mov_b32_e32 v56, v36
	v_mov_b32_e32 v57, v62
	global_store_dwordx2 v[156:157], v[86:87], off
	v_pk_fma_f32 v[58:59], v[58:59], v[92:93], v[106:107]
	v_pk_fma_f32 v[64:65], v[64:65], v[90:91], v[104:105]
	v_pk_add_f32 v[66:67], v[114:115], 1.0 op_sel_hi:[1,0]
	v_pk_add_f32 v[86:87], v[112:113], 1.0 op_sel_hi:[1,0]
	v_mov_b32_e32 v36, v63
	s_waitcnt lgkmcnt(8)
	v_pk_fma_f32 v[58:59], v[58:59], v[66:67], v[122:123]
	v_pk_fma_f32 v[64:65], v[64:65], v[86:87], v[120:121]
	v_pk_mul_f32 v[36:37], v[36:37], v[10:11] op_sel_hi:[1,0]
	v_pk_mul_f32 v[56:57], v[56:57], v[10:11] op_sel_hi:[1,0]
	v_cvt_pk_bf16_f32 v64, v64, v65
	v_cvt_pk_bf16_f32 v65, v58, v59
	s_waitcnt lgkmcnt(5)
; #define LAS __attribute__((address_space(3)))
; __device__ __forceinline__ unsigned cvt_pk_bf16(float lo, float hi) { const f32x2 v = (f32x2){lo, hi}; const bf16v2 b = __builtin_convertvector(v, bf16v2); return __builtin_bit_cast(unsigned, b); }
; template <int PH>
; __device__ __forceinline__ void ln_pass(const Params& p, LAS unsigned char* lds, unsigned char* ws, float* Yx, float* Yc, const float* modv, const float* lng, const float* lnb, f32x2* st1, f32x2* st2, bf16_t* R0, int gw, int NGW, int lane, int wave) {
;     ...
;                 f32x4 v[8]; float s = 0.f;
; #pragma unroll
;                 for (int q = 0; q < 8; ++q) v[q] = nv[q];
;                 { const int mn = m + NGW < rows ? m + NGW : m; const float* yn = mn < MX ? Yx + (size_t)mn * D : p.in[I_CTX] + (size_t)(mn - MX) * D;
; #pragma unroll
;                   for (int q = 0; q < 8; ++q) nv[q] = *(const f32x4*)(yn + q * 256 + lane * 4); }
;     ...
;                 for (int hq = 0; hq < 2; ++hq) {
;                     f32x4 g4[4], b4[4], s4[4], t4[4];
; #pragma unroll
;                     for (int u = 0; u < 4; ++u) { const int c = (hq * 4 + u) * 256 + lane * 4; g4[u] = *(const LAS f32x4*)(Lg + c); b4[u] = *(const LAS f32x4*)(Lb + c); s4[u] = *(const LAS f32x4*)(Ls + c); t4[u] = *(const LAS f32x4*)(Lt + c); }
; #pragma unroll
;                     for (int u = 0; u < 4; ++u) { const int q = hq * 4 + u, c = q * 256 + lane * 4;
;                         const f32x4 xn = v[q] * rstd * g4[u] + b4[u];
;                         const f32x4 h = xn * (1.0f + s4[u]) + t4[u];
;                         u32x2 w; w.x = cvt_pk_bf16(h[0], h[1]); w.y = cvt_pk_bf16(h[2], h[3]); *(u32x2*)(o + c) = w; }
;                 }
	v_pk_fma_f32 v[36:37], v[36:37], v[126:127], v[134:135]
	v_pk_fma_f32 v[56:57], v[56:57], v[124:125], v[132:133]
	s_waitcnt lgkmcnt(3)
	v_pk_add_f32 v[58:59], v[142:143], 1.0 op_sel_hi:[1,0]
	v_pk_add_f32 v[62:63], v[140:141], 1.0 op_sel_hi:[1,0]
	s_waitcnt lgkmcnt(1)
	v_pk_fma_f32 v[36:37], v[36:37], v[58:59], v[150:151]
	v_pk_fma_f32 v[56:57], v[56:57], v[62:63], v[148:149]
	v_pk_mul_f32 v[18:19], v[18:19], v[10:11] op_sel_hi:[1,0]
	v_cvt_pk_bf16_f32 v56, v56, v57
	v_cvt_pk_bf16_f32 v57, v36, v37
	v_pk_mul_f32 v[16:17], v[16:17], v[10:11] op_sel_hi:[1,0]
	global_store_dwordx2 v[156:157], v[56:57], off offset:1024
	v_pk_fma_f32 v[18:19], v[18:19], v[130:131], v[138:139]
	v_pk_fma_f32 v[16:17], v[16:17], v[128:129], v[136:137]
	v_pk_add_f32 v[36:37], v[146:147], 1.0 op_sel_hi:[1,0]
	v_pk_add_f32 v[56:57], v[144:145], 1.0 op_sel_hi:[1,0]
	s_waitcnt lgkmcnt(0)
	v_pk_fma_f32 v[18:19], v[18:19], v[36:37], v[154:155]
	v_pk_fma_f32 v[16:17], v[16:17], v[56:57], v[152:153]
	global_store_dwordx2 v[156:157], v[64:65], off offset:512
	v_cvt_pk_bf16_f32 v16, v16, v17
	v_cvt_pk_bf16_f32 v17, v18, v19
	global_store_dwordx2 v[156:157], v[16:17], off offset:1536
	v_mov_b32_e32 v15, v60
	ds_read_b128 v[16:19], v95 offset:4096
	ds_read_b128 v[56:59], v95 offset:5120
	ds_read_b128 v[62:65], v95 offset:12288
	ds_read_b128 v[86:89], v95 offset:13312
	ds_read_b128 v[90:93], v95 offset:20480
	ds_read_b128 v[100:103], v95 offset:21504
	ds_read_b128 v[104:107], v95 offset:28672
	ds_read_b128 v[108:111], v95 offset:29696
	ds_read_b128 v[112:115], v95 offset:6144
	ds_read_b128 v[116:119], v95 offset:7168
	ds_read_b128 v[120:123], v95 offset:14336
	ds_read_b128 v[124:127], v95 offset:15360
	ds_read_b128 v[128:131], v95 offset:22528
	ds_read_b128 v[132:135], v95 offset:23552
	ds_read_b128 v[136:139], v95 offset:30720
	ds_read_b128 v[140:143], v95 offset:31744
	v_pk_mul_f32 v[14:15], v[14:15], v[10:11] op_sel_hi:[1,0]
	v_pk_mul_f32 v[12:13], v[12:13], v[10:11] op_sel_hi:[1,0]
	s_waitcnt lgkmcnt(13)
	v_pk_fma_f32 v[14:15], v[14:15], v[18:19], v[64:65]
	v_pk_fma_f32 v[12:13], v[12:13], v[16:17], v[62:63]
	s_waitcnt lgkmcnt(11)
	v_pk_add_f32 v[16:17], v[92:93], 1.0 op_sel_hi:[1,0]
	v_pk_add_f32 v[18:19], v[90:91], 1.0 op_sel_hi:[1,0]
	s_waitcnt lgkmcnt(9)
	v_pk_fma_f32 v[14:15], v[14:15], v[16:17], v[106:107]
	v_pk_fma_f32 v[12:13], v[12:13], v[18:19], v[104:105]
	v_mov_b32_e32 v158, v8
	v_mov_b32_e32 v159, v38
	v_cvt_pk_bf16_f32 v12, v12, v13
	v_cvt_pk_bf16_f32 v13, v14, v15
	v_mov_b32_e32 v8, v39
	global_store_dwordx2 v[156:157], v[12:13], off offset:2048
	v_pk_mul_f32 v[8:9], v[8:9], v[10:11] op_sel_hi:[1,0]
	v_pk_mul_f32 v[12:13], v[158:159], v[10:11] op_sel_hi:[1,0]
	v_pk_fma_f32 v[8:9], v[8:9], v[58:59], v[88:89]
	v_pk_fma_f32 v[12:13], v[12:13], v[56:57], v[86:87]
	v_pk_add_f32 v[14:15], v[102:103], 1.0 op_sel_hi:[1,0]
	v_pk_add_f32 v[16:17], v[100:101], 1.0 op_sel_hi:[1,0]
	s_waitcnt lgkmcnt(8)
	v_pk_fma_f32 v[8:9], v[8:9], v[14:15], v[110:111]
	v_pk_fma_f32 v[12:13], v[12:13], v[16:17], v[108:109]
	v_pk_mul_f32 v[6:7], v[6:7], v[10:11] op_sel_hi:[1,0]
	v_cvt_pk_bf16_f32 v12, v12, v13
	v_cvt_pk_bf16_f32 v13, v8, v9
	v_pk_mul_f32 v[4:5], v[4:5], v[10:11] op_sel_hi:[1,0]
	global_store_dwordx2 v[156:157], v[12:13], off offset:2560
	s_waitcnt lgkmcnt(5)
	v_pk_fma_f32 v[6:7], v[6:7], v[114:115], v[122:123]
	v_pk_fma_f32 v[4:5], v[4:5], v[112:113], v[120:121]
	s_waitcnt lgkmcnt(3)
	v_pk_add_f32 v[8:9], v[130:131], 1.0 op_sel_hi:[1,0]
	v_pk_add_f32 v[12:13], v[128:129], 1.0 op_sel_hi:[1,0]
	s_waitcnt lgkmcnt(1)
	v_pk_fma_f32 v[6:7], v[6:7], v[8:9], v[138:139]
	v_pk_fma_f32 v[4:5], v[4:5], v[12:13], v[136:137]
	v_pk_mul_f32 v[2:3], v[2:3], v[10:11] op_sel_hi:[1,0]
	v_cvt_pk_bf16_f32 v4, v4, v5
	v_cvt_pk_bf16_f32 v5, v6, v7
	v_pk_mul_f32 v[0:1], v[0:1], v[10:11] op_sel_hi:[1,0]
	global_store_dwordx2 v[156:157], v[4:5], off offset:3072
	v_pk_fma_f32 v[2:3], v[2:3], v[118:119], v[126:127]
	v_pk_fma_f32 v[0:1], v[0:1], v[116:117], v[124:125]
	v_pk_add_f32 v[4:5], v[134:135], 1.0 op_sel_hi:[1,0]
	v_pk_add_f32 v[6:7], v[132:133], 1.0 op_sel_hi:[1,0]
	s_waitcnt lgkmcnt(0)
	v_pk_fma_f32 v[2:3], v[2:3], v[4:5], v[142:143]
	v_pk_fma_f32 v[0:1], v[0:1], v[6:7], v[140:141]
	s_add_u32 s22, s22, s8
	v_cvt_pk_bf16_f32 v0, v0, v1
	v_cvt_pk_bf16_f32 v1, v2, v3
	global_store_dwordx2 v[156:157], v[0:1], off offset:3584
	s_waitcnt vmcnt(8)
	v_mov_b64_e32 v[0:1], v[52:53]
	v_mov_b64_e32 v[4:5], v[48:49]
	v_mov_b64_e32 v[8:9], v[44:45]
	v_mov_b64_e32 v[12:13], v[40:41]
	v_mov_b64_e32 v[16:17], v[32:33]
	v_mov_b64_e32 v[38:39], v[30:31]
	v_mov_b64_e32 v[62:63], v[26:27]
	v_mov_b64_e32 v[58:59], v[22:23]
	s_addc_u32 s23, s23, s9
	v_lshl_add_u64 v[82:83], v[82:83], 0, s[10:11]
	s_andn2_b64 vcc, exec, s[20:21]
	v_mov_b64_e32 v[2:3], v[54:55]
	v_mov_b64_e32 v[6:7], v[50:51]
	v_mov_b64_e32 v[10:11], v[46:47]
	v_mov_b64_e32 v[14:15], v[42:43]
	v_mov_b64_e32 v[18:19], v[34:35]
	v_mov_b64_e32 v[36:37], v[28:29]
	v_mov_b64_e32 v[60:61], v[24:25]
	v_mov_b64_e32 v[56:57], v[20:21]
	s_mov_b32 s0, s43
	s_cbranch_vccz .LBB0_385

; template <int PH>
; __device__ __forceinline__ void ln_pass(const Params& p, LAS unsigned char* lds, unsigned char* ws, float* Yx, float* Yc, const float* modv, const float* lng, const float* lnb, f32x2* st1, f32x2* st2, bf16_t* R0, int gw, int NGW, int lane, int wave) {
;     ...
;                 for (int q = 0; q < 8; ++q) s += (v[q][0] + v[q][1]) + (v[q][2] + v[q][3]);
;                 const float mean = wave_sum(s) * (1.0f / D); float s2 = 0.f;
; #pragma unroll
;                 for (int q = 0; q < 8; ++q) { v[q] = v[q] - mean; s2 += (v[q][0] * v[q][0] + v[q][1] * v[q][1]) + (v[q][2] * v[q][2] + v[q][3] * v[q][3]); }
;                 const float rstd = 1.0f / sqrtf(wave_sum(s2) * (1.0f / D) + LN_EPS);
;                 if (lane == 0) st[m] = (f32x2){mean, rstd};
.LBB0_383:
	v_mov_b32_e32 v65, v56
	v_mov_b32_e32 v67, v58
	v_mov_b32_e32 v64, v60
	v_mov_b32_e32 v56, v61
	v_mov_b32_e32 v66, v62
	v_mov_b32_e32 v58, v63
	v_pk_add_f32 v[100:101], v[64:65], v[56:57]
	v_pk_add_f32 v[102:103], v[66:67], v[58:59]
	v_mov_b32_e32 v62, v37
	v_pk_add_f32 v[100:101], v[100:101], v[102:103]
	v_mov_b32_e32 v63, v38
	v_mov_b32_e32 v37, v39
	v_mov_b32_e32 v38, v9
	v_mov_b32_e32 v9, v11
	v_add_f32_e32 v11, 0, v101
	v_add_f32_e32 v61, v100, v11
	v_pk_add_f32 v[100:101], v[62:63], v[36:37]
	v_mov_b32_e32 v86, v13
	v_pk_add_f32 v[100:101], v[100:101], v[100:101] op_sel_hi:[0,1]
	v_mov_b32_e32 v60, v15
	v_add_f32_e32 v13, v16, v17
	v_add_f32_e32 v87, v18, v19
	v_mov_b32_e32 v15, v101
	v_mov_b32_e32 v39, v10
	v_pk_add_f32 v[102:103], v[12:13], v[86:87]
	v_pk_add_f32 v[100:101], v[14:15], v[60:61]
	v_mov_b32_e32 v90, v0
	v_pk_add_f32 v[100:101], v[102:103], v[100:101]
	v_pk_add_f32 v[102:103], v[38:39], v[8:9]
	v_pk_add_f32 v[100:101], v[100:101], v[100:101] op_sel_hi:[0,1]
	v_pk_add_f32 v[102:103], v[102:103], v[102:103] op_sel_hi:[0,1]
	v_mov_b32_e32 v92, v1
	v_mov_b32_e32 v10, v2
	v_mov_b32_e32 v88, v3
	v_add_f32_e32 v91, v4, v5
	v_add_f32_e32 v93, v6, v7
	v_mov_b32_e32 v11, v103
	v_mov_b32_e32 v89, v101
	v_pk_add_f32 v[90:91], v[90:91], v[92:93]
	v_pk_add_f32 v[10:11], v[10:11], v[88:89]
	s_nop 0
	v_pk_add_f32 v[10:11], v[90:91], v[10:11]
	s_nop 0
	v_add_f32_e32 v10, v10, v11
	s_nop 1
	v_add_f32_dpp v10, v10, v10 quad_perm:[1,0,3,2] row_mask:0xf bank_mask:0xf bound_ctrl:1
	s_nop 1
	v_add_f32_dpp v10, v10, v10 quad_perm:[2,3,0,1] row_mask:0xf bank_mask:0xf bound_ctrl:1
	s_nop 1
	v_add_f32_dpp v10, v10, v10 row_half_mirror row_mask:0xf bank_mask:0xf bound_ctrl:1
	s_nop 1
	v_add_f32_dpp v10, v10, v10 row_mirror row_mask:0xf bank_mask:0xf bound_ctrl:1
	ds_bpermute_b32 v11, v96, v10
	s_waitcnt lgkmcnt(0)
	v_add_f32_e32 v10, v10, v11
	ds_bpermute_b32 v11, v97, v10
	s_waitcnt lgkmcnt(0)
	v_add_f32_e32 v11, v10, v11
	v_fmac_f32_e32 v59, 0xba000000, v11
	v_fmac_f32_e32 v57, 0xba000000, v11
	v_fmac_f32_e32 v67, 0xba000000, v11
	v_fmac_f32_e32 v65, 0xba000000, v11
	v_mul_f32_e32 v10, v57, v57
	v_mul_f32_e32 v13, v59, v59
	v_fmac_f32_e32 v10, v65, v65
	v_fmac_f32_e32 v13, v67, v67
	v_fmac_f32_e32 v58, 0xba000000, v11
	v_fmac_f32_e32 v56, 0xba000000, v11
	v_add_f32_e32 v10, v10, v13
	v_fmac_f32_e32 v66, 0xba000000, v11
	v_fmac_f32_e32 v64, 0xba000000, v11
	v_mul_f32_e32 v13, v56, v56
	v_mul_f32_e32 v15, v58, v58
	v_fmac_f32_e32 v13, v64, v64
	v_fmac_f32_e32 v15, v66, v66
	v_add_f32_e32 v13, v13, v15
	v_fmac_f32_e32 v37, 0xba000000, v11
	v_fmac_f32_e32 v62, 0xba000000, v11
	v_add_f32_e32 v10, v10, v13
	v_fmac_f32_e32 v63, 0xba000000, v11
	v_fmac_f32_e32 v36, 0xba000000, v11
	v_mul_f32_e32 v13, v62, v62
	v_mul_f32_e32 v15, v37, v37
	v_fmac_f32_e32 v13, v36, v36
	v_fmac_f32_e32 v15, v63, v63
	v_add_f32_e32 v13, v13, v15
	v_fmac_f32_e32 v19, 0xba000000, v11
	v_fmac_f32_e32 v17, 0xba000000, v11
	v_add_f32_e32 v10, v13, v10
	v_fmac_f32_e32 v18, 0xba000000, v11
	v_fmac_f32_e32 v16, 0xba000000, v11
	v_mul_f32_e32 v13, v17, v17
	v_mul_f32_e32 v15, v19, v19
	v_fmac_f32_e32 v13, v16, v16
	v_fmac_f32_e32 v15, v18, v18
	v_add_f32_e32 v13, v13, v15
	v_fmac_f32_e32 v60, 0xba000000, v11
	v_fmac_f32_e32 v86, 0xba000000, v11
	v_add_f32_e32 v10, v13, v10
	v_fmac_f32_e32 v14, 0xba000000, v11
	v_fmac_f32_e32 v12, 0xba000000, v11
	v_mul_f32_e32 v13, v86, v86
	v_mul_f32_e32 v15, v60, v60
	v_fmac_f32_e32 v13, v12, v12
	v_fmac_f32_e32 v15, v14, v14
	v_add_f32_e32 v13, v13, v15
	v_fmac_f32_e32 v9, 0xba000000, v11
	v_fmac_f32_e32 v38, 0xba000000, v11
	v_add_f32_e32 v10, v13, v10
	v_fmac_f32_e32 v39, 0xba000000, v11
	v_fmac_f32_e32 v8, 0xba000000, v11
	v_mul_f32_e32 v13, v38, v38
	v_mul_f32_e32 v15, v9, v9
	v_fmac_f32_e32 v13, v8, v8
	v_fmac_f32_e32 v15, v39, v39
	v_add_f32_e32 v13, v13, v15
	v_fmac_f32_e32 v7, 0xba000000, v11
	v_fmac_f32_e32 v5, 0xba000000, v11
	v_add_f32_e32 v10, v13, v10
	v_fmac_f32_e32 v6, 0xba000000, v11
	v_fmac_f32_e32 v4, 0xba000000, v11
	v_mul_f32_e32 v13, v5, v5
	v_mul_f32_e32 v15, v7, v7
	v_fmac_f32_e32 v13, v4, v4
	v_fmac_f32_e32 v15, v6, v6
	v_add_f32_e32 v13, v13, v15
	v_fmamk_f32 v3, v11, 0xba000000, v3
	v_fmamk_f32 v1, v11, 0xba000000, v1
	v_add_f32_e32 v10, v13, v10
	v_fmamk_f32 v2, v11, 0xba000000, v2
	v_fmac_f32_e32 v0, 0xba000000, v11
	v_mul_f32_e32 v13, v1, v1
	v_mul_f32_e32 v15, v3, v3
	v_fmac_f32_e32 v13, v0, v0
	v_fmac_f32_e32 v15, v2, v2
	v_add_f32_e32 v13, v13, v15
	v_add_f32_e32 v10, v13, v10
	s_nop 1
	v_add_f32_dpp v10, v10, v10 quad_perm:[1,0,3,2] row_mask:0xf bank_mask:0xf bound_ctrl:1
	s_nop 1
	v_add_f32_dpp v10, v10, v10 quad_perm:[2,3,0,1] row_mask:0xf bank_mask:0xf bound_ctrl:1
	s_nop 1
	v_add_f32_dpp v10, v10, v10 row_half_mirror row_mask:0xf bank_mask:0xf bound_ctrl:1
	s_nop 1
	v_add_f32_dpp v10, v10, v10 row_mirror row_mask:0xf bank_mask:0xf bound_ctrl:1
	ds_bpermute_b32 v13, v96, v10
	s_waitcnt lgkmcnt(0)
	v_add_f32_e32 v10, v10, v13
	ds_bpermute_b32 v13, v97, v10
	s_waitcnt lgkmcnt(0)
	v_add_f32_e32 v10, v10, v13
	v_fmamk_f32 v10, v10, 0x3a000000, v98
	v_mul_f32_e32 v13, 0x4f800000, v10
	v_cmp_gt_f32_e32 vcc, s37, v10
	s_nop 1
	v_cndmask_b32_e32 v10, v10, v13, vcc
	v_sqrt_f32_e32 v13, v10
	s_nop 0
	v_add_u32_e32 v15, -1, v13
	v_fma_f32 v61, -v15, v13, v10
	v_cmp_ge_f32_e64 s[0:1], 0, v61
	v_add_u32_e32 v61, 1, v13
	s_nop 0
	v_cndmask_b32_e64 v15, v13, v15, s[0:1]
	v_fma_f32 v13, -v61, v13, v10
	v_cmp_lt_f32_e64 s[0:1], 0, v13
	s_nop 1
	v_cndmask_b32_e64 v13, v15, v61, s[0:1]
	v_mul_f32_e32 v15, 0x37800000, v13
	v_cndmask_b32_e32 v13, v13, v15, vcc
	v_cmp_class_f32_e32 vcc, v10, v99
	s_nop 1
	v_cndmask_b32_e32 v10, v13, v10, vcc
	v_div_scale_f32 v13, s[0:1], v10, v10, 1.0
	v_rcp_f32_e32 v15, v13
	s_nop 0
	v_fma_f32 v61, -v13, v15, 1.0
	v_fmac_f32_e32 v15, v61, v15
	v_div_scale_f32 v61, vcc, 1.0, v10, 1.0
	v_mul_f32_e32 v85, v61, v15
	v_fma_f32 v87, -v13, v85, v61
	v_fmac_f32_e32 v85, v87, v15
	v_fma_f32 v13, -v13, v85, v61
	v_div_fmas_f32 v13, v13, v15, v85
	v_div_fixup_f32 v10, v13, v10, 1.0
	s_and_saveexec_b64 s[0:1], s[2:3]
	s_cbranch_execz .LBB0_378
	s_add_u32 s24, s88, s22
	v_mul_f32_e32 v88, 0x3a000000, v11
	s_addc_u32 s25, s89, s23
	v_mov_b32_e32 v89, v10
	global_store_dwordx2 v69, v[88:89], s[24:25]
	s_branch .LBB0_378

; #define LAS __attribute__((address_space(3)))
; template <int PH>
; __device__ __forceinline__ void ln_pass(const Params& p, LAS unsigned char* lds, unsigned char* ws, float* Yx, float* Yc, const float* modv, const float* lng, const float* lnb, f32x2* st1, f32x2* st2, bf16_t* R0, int gw, int NGW, int lane, int wave) {
;     constexpr int ph = PH;
;             const int j = ph == 4 ? 1 : 2; const int rows = ph == 4 ? MT : MX;
;             f32x2* st = ph == 4 ? st1 : st2;
;             const float* lg = lng + (j - 1) * D; const float* lb = lnb + (j - 1) * D;
;             LAS float* Lg = (LAS float*)lds; LAS float* Lb = Lg + D; LAS float* Ls = Lb + D; LAS float* Lt = Ls + D;
;             { const int tid_ = (int)threadIdx.x; *(LAS f32x4*)(Lg + tid_ * 4) = *(const f32x4*)(lg + tid_ * 4); *(LAS f32x4*)(Lb + tid_ * 4) = *(const f32x4*)(lb + tid_ * 4); }
;             int cur_mr = -1;
;             f32x4 nv[8];
;             if (gw < rows) { const float* y0 = gw < MX ? Yx + (size_t)gw * D : p.in[I_CTX] + (size_t)(gw - MX) * D;
; #pragma unroll
;                 for (int q = 0; q < 8; ++q) nv[q] = *(const f32x4*)(y0 + q * 256 + lane * 4); }
;             for (int m = gw; m < rows; m += NGW) {
.LBB0_1062:
	s_cmp_lt_i32 s90, 13
	s_cselect_b64 s[0:1], -1, 0
	s_and_b64 s[4:5], s[0:1], s[2:3]
	s_andn2_b64 vcc, exec, s[4:5]
	s_cbranch_vccnz .LBB0_1079
	s_waitcnt vmcnt(0)
	v_mov_b32_e32 v65, 0
	v_mov_b32_e32 v181, v65
	v_lshl_add_u64 v[0:1], s[48:49], 0, v[180:181]
	v_add_co_u32_e32 v0, vcc, 0x2000, v0
	v_lshl_add_u64 v[4:5], s[50:51], 0, v[180:181]
	s_nop 0
	v_addc_co_u32_e32 v1, vcc, 0, v1, vcc
	v_add_co_u32_e32 v4, vcc, 0x2000, v4
	global_load_dwordx4 v[0:3], v[0:1], off
	s_nop 0
	v_addc_co_u32_e32 v5, vcc, 0, v5, vcc
	global_load_dwordx4 v[4:7], v[4:5], off
	v_add_u32_e32 v72, 0, v180
	s_cmpk_gt_i32 s34, 0x7fff
	s_waitcnt vmcnt(0)
	ds_write_b128 v72, v[0:3]
	ds_write_b128 v72, v[4:7] offset:8192
	s_cbranch_scc1 .LBB0_1070
	s_ashr_i32 s35, s34, 31
	s_lshl_b64 s[0:1], s[34:35], 13
	s_add_u32 s0, s86, s0
	v_lshlrev_b32_e32 v64, 4, v240
	s_addc_u32 s1, s87, s1
	v_lshl_add_u64 v[0:1], s[0:1], 0, v[64:65]
	s_movk_i32 s12, 0x1000
	v_add_co_u32_e32 v20, vcc, s12, v0
	global_load_dwordx4 v[44:47], v64, s[0:1]
	global_load_dwordx4 v[40:43], v64, s[0:1] offset:1024
	global_load_dwordx4 v[36:39], v64, s[0:1] offset:2048
	global_load_dwordx4 v[16:19], v64, s[0:1] offset:3072
	v_addc_co_u32_e32 v21, vcc, 0, v1, vcc
	global_load_dwordx4 v[12:15], v[20:21], off
	global_load_dwordx4 v[8:11], v[20:21], off offset:1024
	global_load_dwordx4 v[4:7], v[20:21], off offset:2048
	global_load_dwordx4 v[0:3], v[20:21], off offset:3072
	v_mbcnt_lo_u32_b32 v22, -1, 0
	v_mbcnt_hi_u32_b32 v22, -1, v22
	v_and_b32_e32 v24, 64, v22
	v_xor_b32_e32 v23, 16, v22
	v_add_u32_e32 v24, 64, v24
	v_cmp_lt_i32_e32 vcc, v23, v24
	s_lshl_b64 s[0:1], s[34:35], 3
	s_add_u32 s13, s0, 0x280000
	v_cndmask_b32_e32 v23, v22, v23, vcc
	v_lshlrev_b32_e32 v74, 2, v23
	v_xor_b32_e32 v23, 32, v22
	v_cmp_lt_i32_e32 vcc, v23, v24
	v_lshlrev_b32_e32 v21, 2, v241
	v_lshlrev_b32_e32 v20, 2, v240
	v_cndmask_b32_e32 v22, v22, v23, vcc
	s_addc_u32 s14, s1, 0
	s_ashr_i32 s31, s30, 31
	s_lshl_b64 s[0:1], s[34:35], 12
	v_cmp_eq_u32_e64 s[2:3], 0, v240
	v_add_u32_e32 v73, 0, v64
	s_mov_b32 s17, -1
	v_lshlrev_b32_e32 v75, 2, v22
	s_lshl_b64 s[6:7], s[30:31], 3
	v_lshl_or_b32 v66, v240, 3, s0
	v_mov_b32_e32 v67, s1
	s_lshl_b64 s[8:9], s[30:31], 12
	v_lshlrev_b32_e32 v68, 2, v21
	v_lshlrev_b32_e32 v64, 2, v20
	v_mov_b32_e32 v76, 0x3727c5ac
	s_mov_b32 s15, 0xf800000
	v_mov_b32_e32 v77, 0x260
	s_mov_b32 s16, 0x7600000
	s_mov_b32 s0, s34
	s_waitcnt vmcnt(0)
	s_branch .LBB0_1066

; template <int PH>
; __device__ __forceinline__ void ln_pass(const Params& p, LAS unsigned char* lds, unsigned char* ws, float* Yx, float* Yc, const float* modv, const float* lng, const float* lnb, f32x2* st1, f32x2* st2, bf16_t* R0, int gw, int NGW, int lane, int wave) {
;     ...
;                 f32x4 v[8]; float s = 0.f;
; #pragma unroll
;                 for (int q = 0; q < 8; ++q) v[q] = nv[q];
;                 { const int mn = m + NGW < rows ? m + NGW : m; const float* yn = mn < MX ? Yx + (size_t)mn * D : p.in[I_CTX] + (size_t)(mn - MX) * D;
; #pragma unroll
;                   for (int q = 0; q < 8; ++q) nv[q] = *(const f32x4*)(yn + q * 256 + lane * 4); }
;     ...
;                 for (int q = 0; q < 8; ++q) s += (v[q][0] + v[q][1]) + (v[q][2] + v[q][3]);
;                 const float mean = wave_sum(s) * (1.0f / D); float s2 = 0.f;
.LBB0_1068:
	s_waitcnt vmcnt(9)
	v_mov_b32_e32 v50, v44
	v_mov_b32_e32 v51, v40
	v_mov_b32_e32 v52, v45
	v_mov_b32_e32 v53, v41
	v_pk_add_f32 v[50:51], v[50:51], v[52:53]
	v_mov_b32_e32 v52, v46
	v_mov_b32_e32 v53, v42
	v_mov_b32_e32 v54, v47
	v_mov_b32_e32 v55, v43
	v_pk_add_f32 v[52:53], v[52:53], v[54:55]
	v_mov_b32_e32 v54, v36
	v_pk_add_f32 v[50:51], v[50:51], v[52:53]
	v_mov_b32_e32 v52, v37
	v_mov_b32_e32 v53, v38
	v_mov_b32_e32 v55, v39
	v_pk_add_f32 v[52:53], v[52:53], v[54:55]
	v_add_f32_e32 v50, 0, v50
	v_pk_add_f32 v[52:53], v[52:53], v[52:53] op_sel:[0,1] op_sel_hi:[1,0]
	v_add_f32_e32 v50, v50, v51
	v_add_f32_e32 v54, v16, v17
	v_add_f32_e32 v56, v18, v19
	v_mov_b32_e32 v51, v12
	v_mov_b32_e32 v53, v13
	v_mov_b32_e32 v55, v14
	v_mov_b32_e32 v57, v15
	v_pk_add_f32 v[50:51], v[50:51], v[52:53]
	v_pk_add_f32 v[52:53], v[54:55], v[56:57]
	v_mov_b32_e32 v54, v8
	v_pk_add_f32 v[50:51], v[50:51], v[52:53]
	v_mov_b32_e32 v52, v9
	v_mov_b32_e32 v53, v10
	v_mov_b32_e32 v55, v11
	v_pk_add_f32 v[52:53], v[52:53], v[54:55]
	v_pk_add_f32 v[50:51], v[50:51], v[50:51] op_sel:[0,1] op_sel_hi:[1,0]
	v_pk_add_f32 v[52:53], v[52:53], v[52:53] op_sel:[0,1] op_sel_hi:[1,0]
	s_add_i32 s18, s0, s30
	v_add_f32_e32 v54, v4, v5
	v_add_f32_e32 v56, v6, v7
	v_mov_b32_e32 v51, v0
	v_mov_b32_e32 v53, v1
	v_mov_b32_e32 v55, v2
	v_mov_b32_e32 v57, v3
	s_cmpk_gt_i32 s18, 0x7fff
	v_pk_add_f32 v[50:51], v[50:51], v[52:53]
	v_pk_add_f32 v[52:53], v[54:55], v[56:57]
	s_cselect_b64 s[10:11], -1, 0
	s_cmp_lt_i32 s18, 0x8000
	v_pk_add_f32 v[50:51], v[50:51], v[52:53]
	s_cselect_b32 s0, s18, s0
	v_add_f32_e32 v50, v50, v51
	s_add_i32 s19, s0, 0xffff8000
	s_ashr_i32 s1, s0, 31
	v_add_f32_dpp v50, v50, v50 quad_perm:[1,0,3,2] row_mask:0xf bank_mask:0xf bound_ctrl:1
	s_cmp_lt_i32 s0, 0x8000
	s_cselect_b32 s1, s1, 0
	v_add_f32_dpp v50, v50, v50 quad_perm:[2,3,0,1] row_mask:0xf bank_mask:0xf bound_ctrl:1
	s_cselect_b32 s0, s0, s19
	s_cselect_b32 s19, s87, s41
	v_add_f32_dpp v50, v50, v50 row_half_mirror row_mask:0xf bank_mask:0xf bound_ctrl:1
	s_cselect_b32 s20, s86, s40
	s_lshl_b64 s[0:1], s[0:1], 13
	v_add_f32_dpp v50, v50, v50 row_mirror row_mask:0xf bank_mask:0xf bound_ctrl:1
	s_add_u32 s0, s20, s0
	ds_bpermute_b32 v51, v74, v50
	s_addc_u32 s1, s19, s1
	v_lshl_add_u64 v[48:49], s[0:1], 0, v[64:65]
	v_add_co_u32_e32 v70, vcc, s12, v48
	global_load_dwordx4 v[20:23], v64, s[0:1]
	global_load_dwordx4 v[24:27], v64, s[0:1] offset:1024
	global_load_dwordx4 v[28:31], v64, s[0:1] offset:2048
	global_load_dwordx4 v[32:35], v64, s[0:1] offset:3072
	v_addc_co_u32_e32 v71, vcc, 0, v49, vcc
	s_waitcnt lgkmcnt(0)
	v_add_f32_e32 v69, v50, v51
	global_load_dwordx4 v[48:51], v[70:71], off
	global_load_dwordx4 v[52:55], v[70:71], off offset:1024
	global_load_dwordx4 v[56:59], v[70:71], off offset:2048
	global_load_dwordx4 v[60:63], v[70:71], off offset:3072
	ds_bpermute_b32 v78, v75, v69
	s_waitcnt lgkmcnt(0)
; template <int PH>
; __device__ __forceinline__ void ln_pass(const Params& p, LAS unsigned char* lds, unsigned char* ws, float* Yx, float* Yc, const float* modv, const float* lng, const float* lnb, f32x2* st1, f32x2* st2, bf16_t* R0, int gw, int NGW, int lane, int wave) {
;     ...
;                 const float mean = wave_sum(s) * (1.0f / D); float s2 = 0.f;
; #pragma unroll
;                 for (int q = 0; q < 8; ++q) { v[q] = v[q] - mean; s2 += (v[q][0] * v[q][0] + v[q][1] * v[q][1]) + (v[q][2] * v[q][2] + v[q][3] * v[q][3]); }
;                 const float rstd = 1.0f / sqrtf(wave_sum(s2) * (1.0f / D) + LN_EPS);
;                 if (lane == 0) st[m] = (f32x2){mean, rstd};
	v_add_f32_e32 v69, v69, v78
	v_fmamk_f32 v71, v69, 0xba000000, v47
	v_fmamk_f32 v45, v69, 0xba000000, v45
	v_fmamk_f32 v70, v69, 0xba000000, v46
	v_fmac_f32_e32 v44, 0xba000000, v69
	v_mul_f32_e32 v46, v45, v45
	v_mul_f32_e32 v47, v71, v71
	v_fmac_f32_e32 v46, v44, v44
	v_fmac_f32_e32 v47, v70, v70
	v_add_f32_e32 v78, v46, v47
	v_fmamk_f32 v47, v69, 0xba000000, v43
	v_fmamk_f32 v41, v69, 0xba000000, v41
	v_fmamk_f32 v46, v69, 0xba000000, v42
	v_fmac_f32_e32 v40, 0xba000000, v69
	v_mul_f32_e32 v42, v41, v41
	v_mul_f32_e32 v43, v47, v47
	v_fmac_f32_e32 v42, v40, v40
	v_fmac_f32_e32 v43, v46, v46
	v_add_f32_e32 v42, v42, v43
	v_fmamk_f32 v43, v69, 0xba000000, v39
	v_fmamk_f32 v37, v69, 0xba000000, v37
	v_add_f32_e32 v78, v78, v42
	v_fmamk_f32 v42, v69, 0xba000000, v38
	v_fmac_f32_e32 v36, 0xba000000, v69
	v_mul_f32_e32 v38, v37, v37
	v_mul_f32_e32 v39, v43, v43
	v_fmac_f32_e32 v38, v36, v36
	v_fmac_f32_e32 v39, v42, v42
	v_add_f32_e32 v38, v38, v39
	v_fmamk_f32 v39, v69, 0xba000000, v19
	v_fmamk_f32 v17, v69, 0xba000000, v17
	v_add_f32_e32 v78, v38, v78
	v_fmamk_f32 v38, v69, 0xba000000, v18
	v_fmac_f32_e32 v16, 0xba000000, v69
	v_mul_f32_e32 v18, v17, v17
	v_mul_f32_e32 v19, v39, v39
	v_fmac_f32_e32 v18, v16, v16
	v_fmac_f32_e32 v19, v38, v38
	v_add_f32_e32 v18, v18, v19
	v_fmamk_f32 v15, v69, 0xba000000, v15
	v_fmamk_f32 v13, v69, 0xba000000, v13
	v_add_f32_e32 v18, v18, v78
	v_fmamk_f32 v14, v69, 0xba000000, v14
	v_fmac_f32_e32 v12, 0xba000000, v69
	v_mul_f32_e32 v19, v13, v13
	v_mul_f32_e32 v78, v15, v15
	v_fmac_f32_e32 v19, v12, v12
	v_fmac_f32_e32 v78, v14, v14
	v_add_f32_e32 v19, v19, v78
	v_fmamk_f32 v11, v69, 0xba000000, v11
	v_fmamk_f32 v9, v69, 0xba000000, v9
	v_add_f32_e32 v18, v19, v18
	v_fmamk_f32 v10, v69, 0xba000000, v10
	v_fmac_f32_e32 v8, 0xba000000, v69
	v_mul_f32_e32 v19, v9, v9
	v_mul_f32_e32 v78, v11, v11
	v_fmac_f32_e32 v19, v8, v8
	v_fmac_f32_e32 v78, v10, v10
	v_add_f32_e32 v19, v19, v78
	v_fmamk_f32 v7, v69, 0xba000000, v7
	v_fmamk_f32 v5, v69, 0xba000000, v5
	v_add_f32_e32 v18, v19, v18
	v_fmamk_f32 v6, v69, 0xba000000, v6
	v_fmac_f32_e32 v4, 0xba000000, v69
	v_mul_f32_e32 v19, v5, v5
	v_mul_f32_e32 v78, v7, v7
	v_fmac_f32_e32 v19, v4, v4
	v_fmac_f32_e32 v78, v6, v6
	v_add_f32_e32 v19, v19, v78
	v_fmamk_f32 v3, v69, 0xba000000, v3
	v_fmamk_f32 v1, v69, 0xba000000, v1
	v_add_f32_e32 v18, v19, v18
	v_fmamk_f32 v2, v69, 0xba000000, v2
	v_fmac_f32_e32 v0, 0xba000000, v69
	v_mul_f32_e32 v19, v1, v1
	v_mul_f32_e32 v78, v3, v3
	v_fmac_f32_e32 v19, v0, v0
	v_fmac_f32_e32 v78, v2, v2
	v_add_f32_e32 v19, v19, v78
	v_add_f32_e32 v18, v19, v18
	s_nop 1
	v_add_f32_dpp v18, v18, v18 quad_perm:[1,0,3,2] row_mask:0xf bank_mask:0xf bound_ctrl:1
	s_nop 1
	v_add_f32_dpp v18, v18, v18 quad_perm:[2,3,0,1] row_mask:0xf bank_mask:0xf bound_ctrl:1
	s_nop 1
	v_add_f32_dpp v18, v18, v18 row_half_mirror row_mask:0xf bank_mask:0xf bound_ctrl:1
	s_nop 1
	v_add_f32_dpp v18, v18, v18 row_mirror row_mask:0xf bank_mask:0xf bound_ctrl:1
	ds_bpermute_b32 v19, v74, v18
	s_waitcnt lgkmcnt(0)
	v_add_f32_e32 v18, v18, v19
	ds_bpermute_b32 v19, v75, v18
	s_waitcnt lgkmcnt(0)
	v_add_f32_e32 v18, v18, v19
	v_fmamk_f32 v18, v18, 0x3a000000, v76
	v_mul_f32_e32 v19, 0x4f800000, v18
	v_cmp_gt_f32_e32 vcc, s15, v18
	s_nop 1
	v_cndmask_b32_e32 v18, v18, v19, vcc
	v_sqrt_f32_e32 v19, v18
	s_nop 0
	v_add_u32_e32 v78, -1, v19
	v_fma_f32 v79, -v78, v19, v18
	v_cmp_ge_f32_e64 s[0:1], 0, v79
	v_add_u32_e32 v79, 1, v19
	s_nop 0
	v_cndmask_b32_e64 v78, v19, v78, s[0:1]
	v_fma_f32 v19, -v79, v19, v18
	v_cmp_lt_f32_e64 s[0:1], 0, v19
	s_nop 1
	v_cndmask_b32_e64 v19, v78, v79, s[0:1]
	v_mul_f32_e32 v78, 0x37800000, v19
	v_cndmask_b32_e32 v19, v19, v78, vcc
	v_cmp_class_f32_e32 vcc, v18, v77
	s_nop 1
	v_cndmask_b32_e32 v18, v19, v18, vcc
	v_div_scale_f32 v19, s[0:1], v18, v18, 1.0
	v_rcp_f32_e32 v78, v19
	s_nop 0
	v_fma_f32 v79, -v19, v78, 1.0
	v_fmac_f32_e32 v78, v79, v78
	v_div_scale_f32 v79, vcc, 1.0, v18, 1.0
	v_mul_f32_e32 v80, v79, v78
	v_fma_f32 v81, -v19, v80, v79
	v_fmac_f32_e32 v80, v81, v78
	v_fma_f32 v19, -v19, v80, v79
	v_div_fmas_f32 v19, v19, v78, v80
	v_div_fixup_f32 v18, v19, v18, 1.0
	s_and_saveexec_b64 s[0:1], s[2:3]
	s_cbranch_execz .LBB0_1065
	s_add_u32 s20, s88, s13
	v_mul_f32_e32 v78, 0x3a000000, v69
	s_addc_u32 s21, s89, s14
	v_mov_b32_e32 v79, v18
	global_store_dwordx2 v65, v[78:79], s[20:21]
	s_branch .LBB0_1065
